# seam 4: group-arrival count and conversion count polled together in one loop (one round trip less before phase 5)
# speedup vs baseline: 1.0005x; 1.0005x over previous
; __device__ __forceinline__ unsigned xb_ld(unsigned* p) { return __hip_atomic_load(p, __ATOMIC_RELAXED, __HIP_MEMORY_SCOPE_AGENT); }
; __device__ __forceinline__ unsigned xb_add(unsigned* p, unsigned v) { return __hip_atomic_fetch_add(p, v, __ATOMIC_RELAXED, __HIP_MEMORY_SCOPE_AGENT); }
; __device__ __forceinline__ void grid_barrier(unsigned* barw, int k, volatile LAS unsigned* st) {
;     ...
;         unsigned* sb = barw + 1024 + k * 2304;
;         const unsigned old = xb_add(sb + 64 * x, 1u);
;         if (old + 1u == nloc) {
;             __builtin_amdgcn_fence(__ATOMIC_RELEASE, "agent");
;             asm volatile("s_waitcnt vmcnt(0)" ::: "memory");
;             const unsigned og = xb_add(sb + 2048, 1u);
;             if (og + 1u == nx) xb_add(sb + 2112, 1u);
;             else while (xb_ld(sb + 2112) == 0u) __builtin_amdgcn_s_sleep(1);
;             __builtin_amdgcn_fence(__ATOMIC_ACQUIRE, "agent");
;             xb_add(sb + 1024 + 64 * x, 1u);
;             asm volatile("s_waitcnt vmcnt(0)" ::: "memory");
;         } else {
;             while (xb_ld(sb + 1024 + 64 * x) == 0u) __builtin_amdgcn_s_sleep(1);
;             __builtin_amdgcn_fence(__ATOMIC_ACQUIRE, "agent");
;             asm volatile("s_waitcnt vmcnt(0)" ::: "memory");
;         }
.Lgb2_norel:
	global_atomic_add v0, v1, s[4:5]
	s_add_u32 s10, s78, 0x12c00
	s_addc_u32 s11, s79, 0
.Lgb2_spin:
	global_load_dword v2, v0, s[4:5] sc1
	global_load_dword v1, v0, s[10:11] sc1
	s_waitcnt vmcnt(0)
	v_readfirstlane_b32 s7, v2
	v_readfirstlane_b32 s0, v1
	s_cmp_ge_u32 s7, s6
	s_cbranch_scc0 .Lgb2_again
	s_cmp_ge_u32 s0, 128
	s_cbranch_scc1 .Lgb2_pfok
.Lgb2_again:
	s_sleep 1
	s_branch .Lgb2_spin
